# w12: w9 + software-pipelined gla_finalize row loop (prefetch next row's loads into second register set)
# baseline (speedup 1.0000x reference)
; DI f32x4 ldbf4(const bf16* p) { const u32x2 q = *(const u32x2*)p; return (f32x4){__builtin_bit_cast(float, q.x << 16), __builtin_bit_cast(float, q.x & 0xffff0000u), __builtin_bit_cast(float, q.y << 16), __builtin_bit_cast(float, q.y & 0xffff0000u)}; }
; DI void gla_finalize_phase(Frame& F) {
;     ...
;     for (int it0 = 4 * gw; it0 < MP * 4; it0 += 4 * NGW) {
;         const int row = it0 >> 2;
;         f32x4 o[4], gr[4];
; #pragma unroll
;         for (int h = 0; h < 4; ++h) { o[h] = *(const f32x4*)(F.ORAW + (size_t)row * 1024 + h * 256 + 4 * lane); gr[h] = ldbf4(F.G16 + (size_t)row * GLAW + 2048 + h * 256 + 4 * lane); }
.LBB0_1727:
	s_ashr_i32 s0, s16, 2
	s_ashr_i32 s1, s0, 31
	s_mul_i32 s5, s0, 0x1800
	s_lshl_b64 s[2:3], s[0:1], 12
	s_mul_hi_i32 s4, s0, 0x1800
	v_lshl_add_u64 v[6:7], v[24:25], 0, s[2:3]
	s_add_u32 s0, s20, s5
	global_load_dwordx4 v[18:21], v[6:7], off
	global_load_dwordx4 v[14:17], v[6:7], off offset:1024
	global_load_dwordx4 v[10:13], v[6:7], off offset:2048
	s_waitcnt lgkmcnt(0)
	global_load_dwordx4 v[6:9], v[6:7], off offset:3072
	s_addc_u32 s1, s21, s4
	v_lshl_add_u64 v[38:39], v[22:23], 1, s[0:1]
	v_lshl_add_u64 v[40:41], v[38:39], 0, s[14:15]
	v_add_co_u32_e32 v38, vcc, s18, v38
	global_load_dwordx2 v[42:43], v[40:41], off offset:512
	global_load_dwordx2 v[44:45], v[40:41], off offset:1024
	v_addc_co_u32_e32 v39, vcc, 0, v39, vcc
	global_load_dwordx2 v[38:39], v[38:39], off
	s_nop 0
	global_load_dwordx2 v[40:41], v[40:41], off offset:1536
	s_add_i32 s6, s16, s17
	s_cmp_lt_i32 s6, 0x10000
	s_cbranch_scc0 .Lgf_pro_single
	s_ashr_i32 s0, s6, 2
	s_ashr_i32 s1, s0, 31
	s_mul_i32 s5, s0, 0x1800
	s_lshl_b64 s[2:3], s[0:1], 12
	s_mul_hi_i32 s4, s0, 0x1800
	v_lshl_add_u64 v[84:85], v[24:25], 0, s[2:3]
	s_add_u32 s0, s20, s5
	global_load_dwordx4 v[96:99], v[84:85], off
	global_load_dwordx4 v[92:95], v[84:85], off offset:1024
	global_load_dwordx4 v[88:91], v[84:85], off offset:2048
	s_waitcnt lgkmcnt(0)
	global_load_dwordx4 v[84:87], v[84:85], off offset:3072
	s_addc_u32 s1, s21, s4
	v_lshl_add_u64 v[100:101], v[22:23], 1, s[0:1]
	v_lshl_add_u64 v[102:103], v[100:101], 0, s[14:15]
	v_add_co_u32_e32 v100, vcc, s18, v100
	global_load_dwordx2 v[104:105], v[102:103], off offset:512
	global_load_dwordx2 v[106:107], v[102:103], off offset:1024
	v_addc_co_u32_e32 v101, vcc, 0, v101, vcc
	global_load_dwordx2 v[100:101], v[100:101], off
	s_nop 0
	global_load_dwordx2 v[102:103], v[102:103], off offset:1536
	s_waitcnt vmcnt(8)
	s_branch .Lgf_A

; DI unsigned pk2(float lo, float hi) { f32x2 v = {lo, hi}; bf16x2_t b = __builtin_convertvector(v, bf16x2_t); return __builtin_bit_cast(unsigned, b); }
; DI float siluf_(float x) { return x * sigmoidf_(x); }
; DI f32x4 ldbf4(const bf16* p) { const u32x2 q = *(const u32x2*)p; return (f32x4){__builtin_bit_cast(float, q.x << 16), __builtin_bit_cast(float, q.x & 0xffff0000u), __builtin_bit_cast(float, q.y << 16), __builtin_bit_cast(float, q.y & 0xffff0000u)}; }
; DI void gla_finalize_phase(Frame& F) {
;     ...
;         for (int h = 0; h < 4; ++h) { o[h] = *(const f32x4*)(F.ORAW + (size_t)row * 1024 + h * 256 + 4 * lane); gr[h] = ldbf4(F.G16 + (size_t)row * GLAW + 2048 + h * 256 + 4 * lane); }
; #pragma unroll
;         for (int h = 0; h < 4; ++h) {
;             const float ss = wave_sum((o[h][0] * o[h][0] + o[h][1] * o[h][1]) + (o[h][2] * o[h][2] + o[h][3] * o[h][3]));
;             const float rs = 1.f / sqrtf(ss * (1.f / 256.f) + LN_EPS);
;             u32x2 wv; wv.x = pk2(o[h][0] * rs * gn[0] * siluf_(gr[h][0]), o[h][1] * rs * gn[1] * siluf_(gr[h][1])); wv.y = pk2(o[h][2] * rs * gn[2] * siluf_(gr[h][2]), o[h][3] * rs * gn[3] * siluf_(gr[h][3]));
.Lgf_A:
	s_waitcnt vmcnt(19)
	v_pk_mul_f32 v[46:47], v[20:21], v[20:21]
	v_pk_mul_f32 v[48:49], v[18:19], v[18:19]
	s_waitcnt vmcnt(18)
	v_pk_mul_f32 v[50:51], v[16:17], v[16:17]
	v_pk_mul_f32 v[52:53], v[14:15], v[14:15]
	s_waitcnt vmcnt(17)
	v_pk_mul_f32 v[54:55], v[12:13], v[12:13]
	v_pk_mul_f32 v[56:57], v[10:11], v[10:11]
	v_pk_mov_b32 v[62:63], v[48:49], v[46:47] op_sel:[1,0]
	v_mov_b32_e32 v49, v47
	s_waitcnt vmcnt(16)
	v_pk_mul_f32 v[58:59], v[8:9], v[8:9]
	v_pk_mul_f32 v[60:61], v[6:7], v[6:7]
	v_pk_mov_b32 v[46:47], v[52:53], v[50:51] op_sel:[1,0]
	v_mov_b32_e32 v53, v51
	v_pk_mov_b32 v[50:51], v[56:57], v[54:55] op_sel:[1,0]
	v_mov_b32_e32 v57, v55
	v_pk_add_f32 v[48:49], v[62:63], v[48:49]
	v_pk_mov_b32 v[54:55], v[60:61], v[58:59] op_sel:[1,0]
	v_mov_b32_e32 v61, v59
	v_pk_add_f32 v[46:47], v[46:47], v[52:53]
	v_pk_add_f32 v[50:51], v[50:51], v[56:57]
	v_add_f32_e32 v37, v48, v49
	v_pk_add_f32 v[52:53], v[54:55], v[60:61]
	v_add_f32_e32 v54, v46, v47
	v_add_f32_e32 v55, v50, v51
	ds_bpermute_b32 v57, v1, v37
	s_waitcnt vmcnt(15)
	v_lshlrev_b32_e32 v46, 16, v42
	v_and_b32_e32 v47, 0xffff0000, v42
	v_lshlrev_b32_e32 v42, 16, v43
	v_and_b32_e32 v43, 0xffff0000, v43
	s_waitcnt vmcnt(14)
	v_lshlrev_b32_e32 v48, 16, v44
	v_and_b32_e32 v49, 0xffff0000, v44
	v_lshlrev_b32_e32 v44, 16, v45
	s_waitcnt vmcnt(13)
	v_lshlrev_b32_e32 v50, 16, v38
	v_and_b32_e32 v51, 0xffff0000, v38
	v_lshlrev_b32_e32 v38, 16, v39
	ds_bpermute_b32 v58, v1, v54
	ds_bpermute_b32 v63, v1, v55
	v_add_f32_e32 v56, v52, v53
	v_mul_f32_e32 v59, 0xbfb8aa3b, v46
	v_mul_f32_e32 v60, 0xbfb8aa3b, v47
	v_mul_f32_e32 v61, 0xbfb8aa3b, v42
	v_mul_f32_e32 v62, 0xbfb8aa3b, v43
	v_mul_f32_e32 v65, 0xbfb8aa3b, v49
	v_mul_f32_e32 v66, 0xbfb8aa3b, v44
	v_mul_f32_e32 v70, 0xbfb8aa3b, v51
	v_mul_f32_e32 v71, 0xbfb8aa3b, v38
	v_and_b32_e32 v45, 0xffff0000, v45
	v_and_b32_e32 v39, 0xffff0000, v39
	v_mul_f32_e32 v64, 0xbfb8aa3b, v48
	ds_bpermute_b32 v68, v1, v56
	v_exp_f32_e32 v59, v59
	v_exp_f32_e32 v60, v60
	v_exp_f32_e32 v61, v61
	v_exp_f32_e32 v62, v62
	v_exp_f32_e32 v65, v65
	v_exp_f32_e32 v66, v66
	v_exp_f32_e32 v70, v70
	v_exp_f32_e32 v71, v71
	v_mul_f32_e32 v67, 0xbfb8aa3b, v45
	v_mul_f32_e32 v72, 0xbfb8aa3b, v39
	v_exp_f32_e32 v64, v64
	v_exp_f32_e32 v67, v67
	v_exp_f32_e32 v72, v72
	s_waitcnt lgkmcnt(3)
	v_add_f32_e32 v37, v37, v57
	s_waitcnt lgkmcnt(2)
	v_add_f32_e32 v77, v54, v58
	s_waitcnt lgkmcnt(1)
	v_add_f32_e32 v78, v55, v63
	ds_bpermute_b32 v80, v30, v37
	v_add_f32_e32 v54, 1.0, v59
	v_add_f32_e32 v57, 1.0, v60
	v_add_f32_e32 v58, 1.0, v61
	v_add_f32_e32 v59, 1.0, v62
	v_add_f32_e32 v61, 1.0, v65
	v_add_f32_e32 v62, 1.0, v66
	v_add_f32_e32 v65, 1.0, v70
	v_add_f32_e32 v66, 1.0, v71
	ds_bpermute_b32 v70, v30, v77
	ds_bpermute_b32 v71, v30, v78
	v_add_f32_e32 v60, 1.0, v64
	s_waitcnt lgkmcnt(3)
	v_add_f32_e32 v79, v56, v68
	v_rcp_f32_e32 v54, v54
	v_rcp_f32_e32 v55, v57
	v_rcp_f32_e32 v56, v58
	v_rcp_f32_e32 v57, v59
	v_add_f32_e32 v63, 1.0, v67
	v_add_f32_e32 v67, 1.0, v72
	v_rcp_f32_e32 v58, v60
	v_rcp_f32_e32 v59, v61
	ds_bpermute_b32 v72, v30, v79
	v_rcp_f32_e32 v60, v62
	v_rcp_f32_e32 v61, v63
	s_waitcnt lgkmcnt(3)
	v_add_f32_e32 v37, v37, v80
	v_pk_mul_f32 v[46:47], v[54:55], v[46:47]
	v_pk_mul_f32 v[42:43], v[56:57], v[42:43]
	s_waitcnt lgkmcnt(2)
	v_add_f32_e32 v54, v77, v70
	s_waitcnt lgkmcnt(1)
	v_add_f32_e32 v55, v78, v71
	ds_bpermute_b32 v57, v31, v37
	v_pk_mul_f32 v[48:49], v[58:59], v[48:49]
	ds_bpermute_b32 v58, v31, v54
	ds_bpermute_b32 v59, v31, v55
	s_waitcnt lgkmcnt(3)
	v_add_f32_e32 v56, v79, v72
	v_pk_mul_f32 v[44:45], v[60:61], v[44:45]
	ds_bpermute_b32 v60, v31, v56
	s_waitcnt lgkmcnt(3)
	v_add_f32_e32 v37, v37, v57
	s_waitcnt lgkmcnt(2)
	v_add_f32_e32 v54, v54, v58
	s_waitcnt lgkmcnt(1)
	v_add_f32_e32 v55, v55, v59
	ds_bpermute_b32 v57, v32, v37
	ds_bpermute_b32 v58, v32, v54
	ds_bpermute_b32 v59, v32, v55
	s_waitcnt lgkmcnt(3)
	v_add_f32_e32 v56, v56, v60
	ds_bpermute_b32 v60, v32, v56
	s_waitcnt lgkmcnt(3)
	v_add_f32_e32 v37, v37, v57
	s_waitcnt lgkmcnt(2)
	v_add_f32_e32 v54, v54, v58
	s_waitcnt lgkmcnt(1)
	v_add_f32_e32 v55, v55, v59
	ds_bpermute_b32 v57, v33, v37
	ds_bpermute_b32 v58, v33, v54
	ds_bpermute_b32 v59, v33, v55
	s_waitcnt lgkmcnt(3)
	v_add_f32_e32 v56, v56, v60
	ds_bpermute_b32 v60, v33, v56
	s_waitcnt lgkmcnt(3)
	v_add_f32_e32 v37, v37, v57
	s_waitcnt lgkmcnt(2)
	v_add_f32_e32 v54, v54, v58
	s_waitcnt lgkmcnt(1)
	v_add_f32_e32 v55, v55, v59
	ds_bpermute_b32 v57, v34, v37
	ds_bpermute_b32 v58, v34, v54
	ds_bpermute_b32 v59, v34, v55
	s_waitcnt lgkmcnt(3)
	v_add_f32_e32 v56, v56, v60
	s_waitcnt vmcnt(12)
	v_lshlrev_b32_e32 v52, 16, v40
	v_and_b32_e32 v53, 0xffff0000, v40
	v_lshlrev_b32_e32 v40, 16, v41
	v_and_b32_e32 v41, 0xffff0000, v41
	ds_bpermute_b32 v60, v34, v56
	v_mul_f32_e32 v69, 0xbfb8aa3b, v50
	v_mul_f32_e32 v73, 0xbfb8aa3b, v52
	v_mul_f32_e32 v74, 0xbfb8aa3b, v53
	v_mul_f32_e32 v75, 0xbfb8aa3b, v40
	v_mul_f32_e32 v76, 0xbfb8aa3b, v41
	v_exp_f32_e32 v69, v69
	v_exp_f32_e32 v73, v73
	v_exp_f32_e32 v74, v74
	v_exp_f32_e32 v75, v75
	v_exp_f32_e32 v76, v76
	s_waitcnt lgkmcnt(3)
	v_add_f32_e32 v37, v37, v57
	s_waitcnt lgkmcnt(2)
	v_add_f32_e32 v54, v54, v58
	s_waitcnt lgkmcnt(1)
	v_add_f32_e32 v55, v55, v59
	v_fmamk_f32 v37, v37, 0x3b800000, v35
	v_fmamk_f32 v54, v54, 0x3b800000, v35
	v_fmamk_f32 v55, v55, 0x3b800000, v35
	v_mul_f32_e32 v57, 0x4f800000, v37
	v_cmp_gt_f32_e64 s[4:5], s19, v37
	s_waitcnt lgkmcnt(0)
; DI unsigned pk2(float lo, float hi) { f32x2 v = {lo, hi}; bf16x2_t b = __builtin_convertvector(v, bf16x2_t); return __builtin_bit_cast(unsigned, b); }
; DI float siluf_(float x) { return x * sigmoidf_(x); }
; DI void gla_finalize_phase(Frame& F) {
;     ...
;             const float ss = wave_sum((o[h][0] * o[h][0] + o[h][1] * o[h][1]) + (o[h][2] * o[h][2] + o[h][3] * o[h][3]));
;             const float rs = 1.f / sqrtf(ss * (1.f / 256.f) + LN_EPS);
;             u32x2 wv; wv.x = pk2(o[h][0] * rs * gn[0] * siluf_(gr[h][0]), o[h][1] * rs * gn[1] * siluf_(gr[h][1])); wv.y = pk2(o[h][2] * rs * gn[2] * siluf_(gr[h][2]), o[h][3] * rs * gn[3] * siluf_(gr[h][3]));
;             *(u32x2*)(F.MIX + (size_t)row * DM + h * 256 + 4 * lane) = wv; }
;     }
	v_add_f32_e32 v56, v56, v60
	v_mul_f32_e32 v58, 0x4f800000, v54
	v_cmp_gt_f32_e32 vcc, s19, v54
	v_mul_f32_e32 v59, 0x4f800000, v55
	v_cmp_gt_f32_e64 s[0:1], s19, v55
	v_cndmask_b32_e64 v37, v37, v57, s[4:5]
	v_add_f32_e32 v64, 1.0, v69
	v_add_f32_e32 v68, 1.0, v73
	v_add_f32_e32 v69, 1.0, v74
	v_add_f32_e32 v73, 1.0, v75
	v_add_f32_e32 v74, 1.0, v76
	v_fmamk_f32 v56, v56, 0x3b800000, v35
	v_cndmask_b32_e32 v54, v54, v58, vcc
	v_cndmask_b32_e64 v55, v55, v59, s[0:1]
	v_sqrt_f32_e32 v57, v37
	v_rcp_f32_e32 v62, v64
	v_rcp_f32_e32 v63, v65
	v_rcp_f32_e32 v64, v66
	v_rcp_f32_e32 v65, v67
	v_rcp_f32_e32 v66, v68
	v_rcp_f32_e32 v67, v69
	v_rcp_f32_e32 v68, v73
	v_rcp_f32_e32 v69, v74
	v_mul_f32_e32 v60, 0x4f800000, v56
	v_cmp_gt_f32_e64 s[2:3], s19, v56
	v_sqrt_f32_e32 v58, v54
	v_sqrt_f32_e32 v59, v55
	v_cndmask_b32_e64 v56, v56, v60, s[2:3]
	v_sqrt_f32_e32 v60, v56
	v_add_u32_e32 v61, -1, v57
	v_pk_mul_f32 v[50:51], v[62:63], v[50:51]
	v_pk_mul_f32 v[38:39], v[64:65], v[38:39]
	v_pk_mul_f32 v[40:41], v[68:69], v[40:41]
	v_add_u32_e32 v62, 1, v57
	v_add_u32_e32 v63, -1, v58
	v_add_u32_e32 v65, -1, v59
	v_fma_f32 v69, -v61, v57, v37
	v_pk_mul_f32 v[52:53], v[66:67], v[52:53]
	v_add_u32_e32 v64, 1, v58
	v_add_u32_e32 v66, 1, v59
	v_fma_f32 v70, -v62, v57, v37
	v_fma_f32 v71, -v63, v58, v54
	v_fma_f32 v73, -v65, v59, v55
	v_cmp_ge_f32_e64 s[6:7], 0, v69
	v_add_u32_e32 v67, -1, v60
	v_fma_f32 v72, -v64, v58, v54
	v_fma_f32 v74, -v66, v59, v55
	v_cndmask_b32_e64 v57, v57, v61, s[6:7]
	v_cmp_ge_f32_e64 s[6:7], 0, v71
	v_cmp_ge_f32_e64 s[8:9], 0, v73
	v_cmp_lt_f32_e64 s[12:13], 0, v70
	v_add_u32_e32 v68, 1, v60
	v_fma_f32 v75, -v67, v60, v56
	v_cndmask_b32_e64 v58, v58, v63, s[6:7]
	v_cmp_lt_f32_e64 s[6:7], 0, v72
	v_cndmask_b32_e64 v59, v59, v65, s[8:9]
	v_cmp_lt_f32_e64 s[8:9], 0, v74
	v_cndmask_b32_e64 v57, v57, v62, s[12:13]
	v_fma_f32 v76, -v68, v60, v56
	v_cmp_ge_f32_e64 s[10:11], 0, v75
	v_cndmask_b32_e64 v58, v58, v64, s[6:7]
	v_cndmask_b32_e64 v59, v59, v66, s[8:9]
	v_mul_f32_e32 v61, 0x37800000, v57
	v_cndmask_b32_e64 v60, v60, v67, s[10:11]
	v_cmp_lt_f32_e64 s[10:11], 0, v76
	v_mul_f32_e32 v62, 0x37800000, v58
	v_mul_f32_e32 v63, 0x37800000, v59
	v_cndmask_b32_e64 v57, v57, v61, s[4:5]
	v_cmp_class_f32_e64 s[4:5], v37, v36
	v_cndmask_b32_e64 v60, v60, v68, s[10:11]
	v_cndmask_b32_e32 v58, v58, v62, vcc
	v_cmp_class_f32_e32 vcc, v54, v36
	v_cndmask_b32_e64 v59, v59, v63, s[0:1]
	v_cmp_class_f32_e64 s[0:1], v55, v36
	v_cndmask_b32_e64 v37, v57, v37, s[4:5]
	v_mul_f32_e32 v64, 0x37800000, v60
	v_cndmask_b32_e32 v57, v58, v54, vcc
	v_cndmask_b32_e64 v55, v59, v55, s[0:1]
	v_div_scale_f32 v54, s[0:1], v37, v37, 1.0
	v_cndmask_b32_e64 v60, v60, v64, s[2:3]
	v_cmp_class_f32_e64 s[2:3], v56, v36
	v_div_scale_f32 v59, s[0:1], v57, v57, 1.0
	v_rcp_f32_e32 v65, v54
	v_cndmask_b32_e64 v56, v60, v56, s[2:3]
	v_div_scale_f32 v61, s[2:3], v55, v55, 1.0
	v_rcp_f32_e32 v66, v59
	v_div_scale_f32 v63, s[4:5], v56, v56, 1.0
	v_rcp_f32_e32 v67, v61
	v_rcp_f32_e32 v68, v63
	v_fma_f32 v69, -v54, v65, 1.0
	v_div_scale_f32 v58, vcc, 1.0, v37, 1.0
	v_fma_f32 v70, -v59, v66, 1.0
	v_fmac_f32_e32 v65, v69, v65
	v_div_scale_f32 v60, s[0:1], 1.0, v57, 1.0
	v_fma_f32 v71, -v61, v67, 1.0
	v_fmac_f32_e32 v66, v70, v66
	v_mul_f32_e32 v69, v58, v65
	v_div_scale_f32 v62, s[2:3], 1.0, v55, 1.0
	v_fma_f32 v72, -v63, v68, 1.0
	v_fmac_f32_e32 v67, v71, v67
	v_mul_f32_e32 v70, v60, v66
	v_fma_f32 v73, -v54, v69, v58
	v_div_scale_f32 v64, s[4:5], 1.0, v56, 1.0
	v_fmac_f32_e32 v68, v72, v68
	v_mul_f32_e32 v71, v62, v67
	v_fma_f32 v74, -v59, v70, v60
	v_fmac_f32_e32 v69, v73, v65
	v_mul_f32_e32 v72, v64, v68
	v_fma_f32 v75, -v61, v71, v62
	v_fmac_f32_e32 v70, v74, v66
	v_fma_f32 v54, -v54, v69, v58
	v_fma_f32 v76, -v63, v72, v64
	v_fmac_f32_e32 v71, v75, v67
	v_fma_f32 v58, -v59, v70, v60
	v_div_fmas_f32 v54, v54, v65, v69
	s_mov_b64 vcc, s[0:1]
	v_fmac_f32_e32 v72, v76, v68
	v_fma_f32 v59, -v61, v71, v62
	v_div_fixup_f32 v54, v54, v37, 1.0
	v_div_fmas_f32 v37, v58, v66, v70
	s_mov_b64 vcc, s[2:3]
	v_fma_f32 v60, -v63, v72, v64
	v_pk_mul_f32 v[18:19], v[18:19], v[54:55] op_sel_hi:[1,0]
	v_pk_mul_f32 v[20:21], v[20:21], v[54:55] op_sel_hi:[1,0]
	v_div_fixup_f32 v54, v37, v57, 1.0
	v_div_fmas_f32 v37, v59, v67, v71
	s_mov_b64 vcc, s[4:5]
	v_pk_mul_f32 v[20:21], v[4:5], v[20:21]
	v_pk_mul_f32 v[14:15], v[14:15], v[54:55] op_sel_hi:[1,0]
	v_pk_mul_f32 v[16:17], v[16:17], v[54:55] op_sel_hi:[1,0]
	v_div_fixup_f32 v54, v37, v55, 1.0
	v_div_fmas_f32 v37, v60, v68, v72
	v_pk_mul_f32 v[20:21], v[38:39], v[20:21]
	v_div_fixup_f32 v38, v37, v56, 1.0
	v_pk_mul_f32 v[10:11], v[10:11], v[54:55] op_sel_hi:[1,0]
	v_pk_mul_f32 v[12:13], v[12:13], v[54:55] op_sel_hi:[1,0]
	v_pk_mul_f32 v[6:7], v[6:7], v[38:39] op_sel_hi:[1,0]
	v_pk_mul_f32 v[8:9], v[8:9], v[38:39] op_sel_hi:[1,0]
	v_pk_mul_f32 v[18:19], v[2:3], v[18:19]
	v_pk_mul_f32 v[14:15], v[2:3], v[14:15]
	v_pk_mul_f32 v[16:17], v[4:5], v[16:17]
	v_pk_mul_f32 v[10:11], v[2:3], v[10:11]
	v_pk_mul_f32 v[12:13], v[4:5], v[12:13]
	v_pk_mul_f32 v[6:7], v[2:3], v[6:7]
	v_pk_mul_f32 v[8:9], v[4:5], v[8:9]
	v_pk_mul_f32 v[18:19], v[50:51], v[18:19]
	v_pk_mul_f32 v[14:15], v[46:47], v[14:15]
	v_pk_mul_f32 v[16:17], v[42:43], v[16:17]
	v_pk_mul_f32 v[10:11], v[48:49], v[10:11]
	v_pk_mul_f32 v[12:13], v[44:45], v[12:13]
	v_pk_mul_f32 v[6:7], v[52:53], v[6:7]
	v_pk_mul_f32 v[8:9], v[40:41], v[8:9]
	v_cvt_pk_bf16_f32 v18, v18, v19
	v_cvt_pk_bf16_f32 v19, v20, v21
	v_cvt_pk_bf16_f32 v14, v14, v15
	v_cvt_pk_bf16_f32 v15, v16, v17
	v_cvt_pk_bf16_f32 v10, v10, v11
	v_cvt_pk_bf16_f32 v11, v12, v13
	v_cvt_pk_bf16_f32 v6, v6, v7
	v_cvt_pk_bf16_f32 v7, v8, v9
	s_ashr_i32 s0, s16, 2
	s_ashr_i32 s1, s0, 31
	s_lshl_b64 s[2:3], s[0:1], 12
	v_lshl_add_u64 v[28:29], v[26:27], 0, s[2:3]
	global_store_dwordx2 v[28:29], v[18:19], off
	global_store_dwordx2 v[28:29], v[14:15], off offset:512
	global_store_dwordx2 v[28:29], v[10:11], off offset:1024
	global_store_dwordx2 v[28:29], v[6:7], off offset:1536
	s_add_i32 s16, s16, s17
	s_cmp_lt_i32 s16, 0x10000
	s_cbranch_scc0 .LBB0_1728
	s_add_i32 s6, s16, s17
	s_cmp_lt_i32 s6, 0x10000
	s_cbranch_scc0 .Lgf_A_nopf
	s_ashr_i32 s0, s6, 2
	s_ashr_i32 s1, s0, 31
	s_mul_i32 s5, s0, 0x1800
	s_lshl_b64 s[2:3], s[0:1], 12
	s_mul_hi_i32 s4, s0, 0x1800
	v_lshl_add_u64 v[6:7], v[24:25], 0, s[2:3]
	s_add_u32 s0, s20, s5
	global_load_dwordx4 v[18:21], v[6:7], off
	global_load_dwordx4 v[14:17], v[6:7], off offset:1024
	global_load_dwordx4 v[10:13], v[6:7], off offset:2048
	s_waitcnt lgkmcnt(0)
	global_load_dwordx4 v[6:9], v[6:7], off offset:3072
	s_addc_u32 s1, s21, s4
	v_lshl_add_u64 v[38:39], v[22:23], 1, s[0:1]
	v_lshl_add_u64 v[40:41], v[38:39], 0, s[14:15]
	v_add_co_u32_e32 v38, vcc, s18, v38
	global_load_dwordx2 v[42:43], v[40:41], off offset:512
	global_load_dwordx2 v[44:45], v[40:41], off offset:1024
	v_addc_co_u32_e32 v39, vcc, 0, v39, vcc
	global_load_dwordx2 v[38:39], v[38:39], off
	s_nop 0
	global_load_dwordx2 v[40:41], v[40:41], off offset:1536
	s_branch .Lgf_B
; DI unsigned pk2(float lo, float hi) { f32x2 v = {lo, hi}; bf16x2_t b = __builtin_convertvector(v, bf16x2_t); return __builtin_bit_cast(unsigned, b); }
; DI float siluf_(float x) { return x * sigmoidf_(x); }
; DI f32x4 ldbf4(const bf16* p) { const u32x2 q = *(const u32x2*)p; return (f32x4){__builtin_bit_cast(float, q.x << 16), __builtin_bit_cast(float, q.x & 0xffff0000u), __builtin_bit_cast(float, q.y << 16), __builtin_bit_cast(float, q.y & 0xffff0000u)}; }
; DI void gla_finalize_phase(Frame& F) {
;     ...
;         for (int h = 0; h < 4; ++h) { o[h] = *(const f32x4*)(F.ORAW + (size_t)row * 1024 + h * 256 + 4 * lane); gr[h] = ldbf4(F.G16 + (size_t)row * GLAW + 2048 + h * 256 + 4 * lane); }
; #pragma unroll
;         for (int h = 0; h < 4; ++h) {
;             const float ss = wave_sum((o[h][0] * o[h][0] + o[h][1] * o[h][1]) + (o[h][2] * o[h][2] + o[h][3] * o[h][3]));
;             const float rs = 1.f / sqrtf(ss * (1.f / 256.f) + LN_EPS);
;             u32x2 wv; wv.x = pk2(o[h][0] * rs * gn[0] * siluf_(gr[h][0]), o[h][1] * rs * gn[1] * siluf_(gr[h][1])); wv.y = pk2(o[h][2] * rs * gn[2] * siluf_(gr[h][2]), o[h][3] * rs * gn[3] * siluf_(gr[h][3]));
.Lgf_A_nopf:
	s_waitcnt vmcnt(4)
.Lgf_B:
	s_waitcnt vmcnt(19)
	v_pk_mul_f32 v[46:47], v[98:99], v[98:99]
	v_pk_mul_f32 v[48:49], v[96:97], v[96:97]
	s_waitcnt vmcnt(18)
	v_pk_mul_f32 v[50:51], v[94:95], v[94:95]
	v_pk_mul_f32 v[52:53], v[92:93], v[92:93]
	s_waitcnt vmcnt(17)
	v_pk_mul_f32 v[54:55], v[90:91], v[90:91]
	v_pk_mul_f32 v[56:57], v[88:89], v[88:89]
	v_pk_mov_b32 v[62:63], v[48:49], v[46:47] op_sel:[1,0]
	v_mov_b32_e32 v49, v47
	s_waitcnt vmcnt(16)
	v_pk_mul_f32 v[58:59], v[86:87], v[86:87]
	v_pk_mul_f32 v[60:61], v[84:85], v[84:85]
	v_pk_mov_b32 v[46:47], v[52:53], v[50:51] op_sel:[1,0]
	v_mov_b32_e32 v53, v51
	v_pk_mov_b32 v[50:51], v[56:57], v[54:55] op_sel:[1,0]
	v_mov_b32_e32 v57, v55
	v_pk_add_f32 v[48:49], v[62:63], v[48:49]
	v_pk_mov_b32 v[54:55], v[60:61], v[58:59] op_sel:[1,0]
	v_mov_b32_e32 v61, v59
	v_pk_add_f32 v[46:47], v[46:47], v[52:53]
	v_pk_add_f32 v[50:51], v[50:51], v[56:57]
	v_add_f32_e32 v37, v48, v49
	v_pk_add_f32 v[52:53], v[54:55], v[60:61]
	v_add_f32_e32 v54, v46, v47
	v_add_f32_e32 v55, v50, v51
	ds_bpermute_b32 v57, v1, v37
	s_waitcnt vmcnt(15)
	v_lshlrev_b32_e32 v46, 16, v104
	v_and_b32_e32 v47, 0xffff0000, v104
	v_lshlrev_b32_e32 v104, 16, v105
	v_and_b32_e32 v105, 0xffff0000, v105
	s_waitcnt vmcnt(14)
	v_lshlrev_b32_e32 v48, 16, v106
	v_and_b32_e32 v49, 0xffff0000, v106
	v_lshlrev_b32_e32 v106, 16, v107
	s_waitcnt vmcnt(13)
	v_lshlrev_b32_e32 v50, 16, v100
	v_and_b32_e32 v51, 0xffff0000, v100
	v_lshlrev_b32_e32 v100, 16, v101
	ds_bpermute_b32 v58, v1, v54
	ds_bpermute_b32 v63, v1, v55
	v_add_f32_e32 v56, v52, v53
	v_mul_f32_e32 v59, 0xbfb8aa3b, v46
	v_mul_f32_e32 v60, 0xbfb8aa3b, v47
	v_mul_f32_e32 v61, 0xbfb8aa3b, v104
	v_mul_f32_e32 v62, 0xbfb8aa3b, v105
	v_mul_f32_e32 v65, 0xbfb8aa3b, v49
	v_mul_f32_e32 v66, 0xbfb8aa3b, v106
	v_mul_f32_e32 v70, 0xbfb8aa3b, v51
	v_mul_f32_e32 v71, 0xbfb8aa3b, v100
	v_and_b32_e32 v107, 0xffff0000, v107
	v_and_b32_e32 v101, 0xffff0000, v101
	v_mul_f32_e32 v64, 0xbfb8aa3b, v48
	ds_bpermute_b32 v68, v1, v56
	v_exp_f32_e32 v59, v59
	v_exp_f32_e32 v60, v60
	v_exp_f32_e32 v61, v61
	v_exp_f32_e32 v62, v62
	v_exp_f32_e32 v65, v65
	v_exp_f32_e32 v66, v66
	v_exp_f32_e32 v70, v70
	v_exp_f32_e32 v71, v71
	v_mul_f32_e32 v67, 0xbfb8aa3b, v107
	v_mul_f32_e32 v72, 0xbfb8aa3b, v101
	v_exp_f32_e32 v64, v64
	v_exp_f32_e32 v67, v67
	v_exp_f32_e32 v72, v72
	s_waitcnt lgkmcnt(3)
	v_add_f32_e32 v37, v37, v57
	s_waitcnt lgkmcnt(2)
	v_add_f32_e32 v77, v54, v58
	s_waitcnt lgkmcnt(1)
	v_add_f32_e32 v78, v55, v63
	ds_bpermute_b32 v80, v30, v37
	v_add_f32_e32 v54, 1.0, v59
	v_add_f32_e32 v57, 1.0, v60
	v_add_f32_e32 v58, 1.0, v61
	v_add_f32_e32 v59, 1.0, v62
	v_add_f32_e32 v61, 1.0, v65
	v_add_f32_e32 v62, 1.0, v66
	v_add_f32_e32 v65, 1.0, v70
	v_add_f32_e32 v66, 1.0, v71
	ds_bpermute_b32 v70, v30, v77
	ds_bpermute_b32 v71, v30, v78
	v_add_f32_e32 v60, 1.0, v64
	s_waitcnt lgkmcnt(3)
	v_add_f32_e32 v79, v56, v68
	v_rcp_f32_e32 v54, v54
	v_rcp_f32_e32 v55, v57
	v_rcp_f32_e32 v56, v58
	v_rcp_f32_e32 v57, v59
	v_add_f32_e32 v63, 1.0, v67
	v_add_f32_e32 v67, 1.0, v72
	v_rcp_f32_e32 v58, v60
	v_rcp_f32_e32 v59, v61
	ds_bpermute_b32 v72, v30, v79
	v_rcp_f32_e32 v60, v62
	v_rcp_f32_e32 v61, v63
	s_waitcnt lgkmcnt(3)
	v_add_f32_e32 v37, v37, v80
	v_pk_mul_f32 v[46:47], v[54:55], v[46:47]
	v_pk_mul_f32 v[104:105], v[56:57], v[104:105]
	s_waitcnt lgkmcnt(2)
	v_add_f32_e32 v54, v77, v70
	s_waitcnt lgkmcnt(1)
	v_add_f32_e32 v55, v78, v71
	ds_bpermute_b32 v57, v31, v37
	v_pk_mul_f32 v[48:49], v[58:59], v[48:49]
	ds_bpermute_b32 v58, v31, v54
	ds_bpermute_b32 v59, v31, v55
	s_waitcnt lgkmcnt(3)
	v_add_f32_e32 v56, v79, v72
	v_pk_mul_f32 v[106:107], v[60:61], v[106:107]
	ds_bpermute_b32 v60, v31, v56
	s_waitcnt lgkmcnt(3)
	v_add_f32_e32 v37, v37, v57
	s_waitcnt lgkmcnt(2)
	v_add_f32_e32 v54, v54, v58
	s_waitcnt lgkmcnt(1)
	v_add_f32_e32 v55, v55, v59
	ds_bpermute_b32 v57, v32, v37
	ds_bpermute_b32 v58, v32, v54
	ds_bpermute_b32 v59, v32, v55
	s_waitcnt lgkmcnt(3)
	v_add_f32_e32 v56, v56, v60
	ds_bpermute_b32 v60, v32, v56
	s_waitcnt lgkmcnt(3)
	v_add_f32_e32 v37, v37, v57
	s_waitcnt lgkmcnt(2)
	v_add_f32_e32 v54, v54, v58
	s_waitcnt lgkmcnt(1)
	v_add_f32_e32 v55, v55, v59
	ds_bpermute_b32 v57, v33, v37
	ds_bpermute_b32 v58, v33, v54
	ds_bpermute_b32 v59, v33, v55
	s_waitcnt lgkmcnt(3)
	v_add_f32_e32 v56, v56, v60
	ds_bpermute_b32 v60, v33, v56
	s_waitcnt lgkmcnt(3)
	v_add_f32_e32 v37, v37, v57
	s_waitcnt lgkmcnt(2)
	v_add_f32_e32 v54, v54, v58
	s_waitcnt lgkmcnt(1)
	v_add_f32_e32 v55, v55, v59
	ds_bpermute_b32 v57, v34, v37
	ds_bpermute_b32 v58, v34, v54
	ds_bpermute_b32 v59, v34, v55
	s_waitcnt lgkmcnt(3)
	v_add_f32_e32 v56, v56, v60
	s_waitcnt vmcnt(12)
	v_lshlrev_b32_e32 v52, 16, v102
	v_and_b32_e32 v53, 0xffff0000, v102
	v_lshlrev_b32_e32 v102, 16, v103
	v_and_b32_e32 v103, 0xffff0000, v103
	ds_bpermute_b32 v60, v34, v56
	v_mul_f32_e32 v69, 0xbfb8aa3b, v50
	v_mul_f32_e32 v73, 0xbfb8aa3b, v52
	v_mul_f32_e32 v74, 0xbfb8aa3b, v53
	v_mul_f32_e32 v75, 0xbfb8aa3b, v102
	v_mul_f32_e32 v76, 0xbfb8aa3b, v103
	v_exp_f32_e32 v69, v69
	v_exp_f32_e32 v73, v73
	v_exp_f32_e32 v74, v74
	v_exp_f32_e32 v75, v75
	v_exp_f32_e32 v76, v76
	s_waitcnt lgkmcnt(3)
	v_add_f32_e32 v37, v37, v57
	s_waitcnt lgkmcnt(2)
	v_add_f32_e32 v54, v54, v58
	s_waitcnt lgkmcnt(1)
	v_add_f32_e32 v55, v55, v59
	v_fmamk_f32 v37, v37, 0x3b800000, v35
	v_fmamk_f32 v54, v54, 0x3b800000, v35
	v_fmamk_f32 v55, v55, 0x3b800000, v35
	v_mul_f32_e32 v57, 0x4f800000, v37
	v_cmp_gt_f32_e64 s[4:5], s19, v37
	s_waitcnt lgkmcnt(0)
; DI unsigned pk2(float lo, float hi) { f32x2 v = {lo, hi}; bf16x2_t b = __builtin_convertvector(v, bf16x2_t); return __builtin_bit_cast(unsigned, b); }
; DI float siluf_(float x) { return x * sigmoidf_(x); }
; DI void gla_finalize_phase(Frame& F) {
;     ...
;             const float ss = wave_sum((o[h][0] * o[h][0] + o[h][1] * o[h][1]) + (o[h][2] * o[h][2] + o[h][3] * o[h][3]));
;             const float rs = 1.f / sqrtf(ss * (1.f / 256.f) + LN_EPS);
;             u32x2 wv; wv.x = pk2(o[h][0] * rs * gn[0] * siluf_(gr[h][0]), o[h][1] * rs * gn[1] * siluf_(gr[h][1])); wv.y = pk2(o[h][2] * rs * gn[2] * siluf_(gr[h][2]), o[h][3] * rs * gn[3] * siluf_(gr[h][3]));
;             *(u32x2*)(F.MIX + (size_t)row * DM + h * 256 + 4 * lane) = wv; }
;     }
	v_add_f32_e32 v56, v56, v60
	v_mul_f32_e32 v58, 0x4f800000, v54
	v_cmp_gt_f32_e32 vcc, s19, v54
	v_mul_f32_e32 v59, 0x4f800000, v55
	v_cmp_gt_f32_e64 s[0:1], s19, v55
	v_cndmask_b32_e64 v37, v37, v57, s[4:5]
	v_add_f32_e32 v64, 1.0, v69
	v_add_f32_e32 v68, 1.0, v73
	v_add_f32_e32 v69, 1.0, v74
	v_add_f32_e32 v73, 1.0, v75
	v_add_f32_e32 v74, 1.0, v76
	v_fmamk_f32 v56, v56, 0x3b800000, v35
	v_cndmask_b32_e32 v54, v54, v58, vcc
	v_cndmask_b32_e64 v55, v55, v59, s[0:1]
	v_sqrt_f32_e32 v57, v37
	v_rcp_f32_e32 v62, v64
	v_rcp_f32_e32 v63, v65
	v_rcp_f32_e32 v64, v66
	v_rcp_f32_e32 v65, v67
	v_rcp_f32_e32 v66, v68
	v_rcp_f32_e32 v67, v69
	v_rcp_f32_e32 v68, v73
	v_rcp_f32_e32 v69, v74
	v_mul_f32_e32 v60, 0x4f800000, v56
	v_cmp_gt_f32_e64 s[2:3], s19, v56
	v_sqrt_f32_e32 v58, v54
	v_sqrt_f32_e32 v59, v55
	v_cndmask_b32_e64 v56, v56, v60, s[2:3]
	v_sqrt_f32_e32 v60, v56
	v_add_u32_e32 v61, -1, v57
	v_pk_mul_f32 v[50:51], v[62:63], v[50:51]
	v_pk_mul_f32 v[100:101], v[64:65], v[100:101]
	v_pk_mul_f32 v[102:103], v[68:69], v[102:103]
	v_add_u32_e32 v62, 1, v57
	v_add_u32_e32 v63, -1, v58
	v_add_u32_e32 v65, -1, v59
	v_fma_f32 v69, -v61, v57, v37
	v_pk_mul_f32 v[52:53], v[66:67], v[52:53]
	v_add_u32_e32 v64, 1, v58
	v_add_u32_e32 v66, 1, v59
	v_fma_f32 v70, -v62, v57, v37
	v_fma_f32 v71, -v63, v58, v54
	v_fma_f32 v73, -v65, v59, v55
	v_cmp_ge_f32_e64 s[6:7], 0, v69
	v_add_u32_e32 v67, -1, v60
	v_fma_f32 v72, -v64, v58, v54
	v_fma_f32 v74, -v66, v59, v55
	v_cndmask_b32_e64 v57, v57, v61, s[6:7]
	v_cmp_ge_f32_e64 s[6:7], 0, v71
	v_cmp_ge_f32_e64 s[8:9], 0, v73
	v_cmp_lt_f32_e64 s[12:13], 0, v70
	v_add_u32_e32 v68, 1, v60
	v_fma_f32 v75, -v67, v60, v56
	v_cndmask_b32_e64 v58, v58, v63, s[6:7]
	v_cmp_lt_f32_e64 s[6:7], 0, v72
	v_cndmask_b32_e64 v59, v59, v65, s[8:9]
	v_cmp_lt_f32_e64 s[8:9], 0, v74
	v_cndmask_b32_e64 v57, v57, v62, s[12:13]
	v_fma_f32 v76, -v68, v60, v56
	v_cmp_ge_f32_e64 s[10:11], 0, v75
	v_cndmask_b32_e64 v58, v58, v64, s[6:7]
	v_cndmask_b32_e64 v59, v59, v66, s[8:9]
	v_mul_f32_e32 v61, 0x37800000, v57
	v_cndmask_b32_e64 v60, v60, v67, s[10:11]
	v_cmp_lt_f32_e64 s[10:11], 0, v76
	v_mul_f32_e32 v62, 0x37800000, v58
	v_mul_f32_e32 v63, 0x37800000, v59
	v_cndmask_b32_e64 v57, v57, v61, s[4:5]
	v_cmp_class_f32_e64 s[4:5], v37, v36
	v_cndmask_b32_e64 v60, v60, v68, s[10:11]
	v_cndmask_b32_e32 v58, v58, v62, vcc
	v_cmp_class_f32_e32 vcc, v54, v36
	v_cndmask_b32_e64 v59, v59, v63, s[0:1]
	v_cmp_class_f32_e64 s[0:1], v55, v36
	v_cndmask_b32_e64 v37, v57, v37, s[4:5]
	v_mul_f32_e32 v64, 0x37800000, v60
	v_cndmask_b32_e32 v57, v58, v54, vcc
	v_cndmask_b32_e64 v55, v59, v55, s[0:1]
	v_div_scale_f32 v54, s[0:1], v37, v37, 1.0
	v_cndmask_b32_e64 v60, v60, v64, s[2:3]
	v_cmp_class_f32_e64 s[2:3], v56, v36
	v_div_scale_f32 v59, s[0:1], v57, v57, 1.0
	v_rcp_f32_e32 v65, v54
	v_cndmask_b32_e64 v56, v60, v56, s[2:3]
	v_div_scale_f32 v61, s[2:3], v55, v55, 1.0
	v_rcp_f32_e32 v66, v59
	v_div_scale_f32 v63, s[4:5], v56, v56, 1.0
	v_rcp_f32_e32 v67, v61
	v_rcp_f32_e32 v68, v63
	v_fma_f32 v69, -v54, v65, 1.0
	v_div_scale_f32 v58, vcc, 1.0, v37, 1.0
	v_fma_f32 v70, -v59, v66, 1.0
	v_fmac_f32_e32 v65, v69, v65
	v_div_scale_f32 v60, s[0:1], 1.0, v57, 1.0
	v_fma_f32 v71, -v61, v67, 1.0
	v_fmac_f32_e32 v66, v70, v66
	v_mul_f32_e32 v69, v58, v65
	v_div_scale_f32 v62, s[2:3], 1.0, v55, 1.0
	v_fma_f32 v72, -v63, v68, 1.0
	v_fmac_f32_e32 v67, v71, v67
	v_mul_f32_e32 v70, v60, v66
	v_fma_f32 v73, -v54, v69, v58
	v_div_scale_f32 v64, s[4:5], 1.0, v56, 1.0
	v_fmac_f32_e32 v68, v72, v68
	v_mul_f32_e32 v71, v62, v67
	v_fma_f32 v74, -v59, v70, v60
	v_fmac_f32_e32 v69, v73, v65
	v_mul_f32_e32 v72, v64, v68
	v_fma_f32 v75, -v61, v71, v62
	v_fmac_f32_e32 v70, v74, v66
	v_fma_f32 v54, -v54, v69, v58
	v_fma_f32 v76, -v63, v72, v64
	v_fmac_f32_e32 v71, v75, v67
	v_fma_f32 v58, -v59, v70, v60
	v_div_fmas_f32 v54, v54, v65, v69
	s_mov_b64 vcc, s[0:1]
	v_fmac_f32_e32 v72, v76, v68
	v_fma_f32 v59, -v61, v71, v62
	v_div_fixup_f32 v54, v54, v37, 1.0
	v_div_fmas_f32 v37, v58, v66, v70
	s_mov_b64 vcc, s[2:3]
	v_fma_f32 v60, -v63, v72, v64
	v_pk_mul_f32 v[96:97], v[96:97], v[54:55] op_sel_hi:[1,0]
	v_pk_mul_f32 v[98:99], v[98:99], v[54:55] op_sel_hi:[1,0]
	v_div_fixup_f32 v54, v37, v57, 1.0
	v_div_fmas_f32 v37, v59, v67, v71
	s_mov_b64 vcc, s[4:5]
	v_pk_mul_f32 v[98:99], v[4:5], v[98:99]
	v_pk_mul_f32 v[92:93], v[92:93], v[54:55] op_sel_hi:[1,0]
	v_pk_mul_f32 v[94:95], v[94:95], v[54:55] op_sel_hi:[1,0]
	v_div_fixup_f32 v54, v37, v55, 1.0
	v_div_fmas_f32 v37, v60, v68, v72
	v_pk_mul_f32 v[98:99], v[100:101], v[98:99]
	v_div_fixup_f32 v100, v37, v56, 1.0
	v_pk_mul_f32 v[88:89], v[88:89], v[54:55] op_sel_hi:[1,0]
	v_pk_mul_f32 v[90:91], v[90:91], v[54:55] op_sel_hi:[1,0]
	v_pk_mul_f32 v[84:85], v[84:85], v[100:101] op_sel_hi:[1,0]
	v_pk_mul_f32 v[86:87], v[86:87], v[100:101] op_sel_hi:[1,0]
	v_pk_mul_f32 v[96:97], v[2:3], v[96:97]
	v_pk_mul_f32 v[92:93], v[2:3], v[92:93]
	v_pk_mul_f32 v[94:95], v[4:5], v[94:95]
	v_pk_mul_f32 v[88:89], v[2:3], v[88:89]
	v_pk_mul_f32 v[90:91], v[4:5], v[90:91]
	v_pk_mul_f32 v[84:85], v[2:3], v[84:85]
	v_pk_mul_f32 v[86:87], v[4:5], v[86:87]
	v_pk_mul_f32 v[96:97], v[50:51], v[96:97]
	v_pk_mul_f32 v[92:93], v[46:47], v[92:93]
	v_pk_mul_f32 v[94:95], v[104:105], v[94:95]
	v_pk_mul_f32 v[88:89], v[48:49], v[88:89]
	v_pk_mul_f32 v[90:91], v[106:107], v[90:91]
	v_pk_mul_f32 v[84:85], v[52:53], v[84:85]
	v_pk_mul_f32 v[86:87], v[102:103], v[86:87]
	v_cvt_pk_bf16_f32 v96, v96, v97
	v_cvt_pk_bf16_f32 v97, v98, v99
	v_cvt_pk_bf16_f32 v92, v92, v93
	v_cvt_pk_bf16_f32 v93, v94, v95
	v_cvt_pk_bf16_f32 v88, v88, v89
	v_cvt_pk_bf16_f32 v89, v90, v91
	v_cvt_pk_bf16_f32 v84, v84, v85
	v_cvt_pk_bf16_f32 v85, v86, v87
	s_ashr_i32 s0, s16, 2
	s_ashr_i32 s1, s0, 31
	s_lshl_b64 s[2:3], s[0:1], 12
	v_lshl_add_u64 v[28:29], v[26:27], 0, s[2:3]
	global_store_dwordx2 v[28:29], v[96:97], off
	global_store_dwordx2 v[28:29], v[92:93], off offset:512
	global_store_dwordx2 v[28:29], v[88:89], off offset:1024
	global_store_dwordx2 v[28:29], v[84:85], off offset:1536
	s_add_i32 s16, s16, s17
	s_cmp_lt_i32 s16, 0x10000
	s_cbranch_scc0 .LBB0_1728
; DI f32x4 ldbf4(const bf16* p) { const u32x2 q = *(const u32x2*)p; return (f32x4){__builtin_bit_cast(float, q.x << 16), __builtin_bit_cast(float, q.x & 0xffff0000u), __builtin_bit_cast(float, q.y << 16), __builtin_bit_cast(float, q.y & 0xffff0000u)}; }
; DI void gla_finalize_phase(Frame& F) {
;     ...
;     for (int it0 = 4 * gw; it0 < MP * 4; it0 += 4 * NGW) {
;         const int row = it0 >> 2;
;         f32x4 o[4], gr[4];
; #pragma unroll
;         for (int h = 0; h < 4; ++h) { o[h] = *(const f32x4*)(F.ORAW + (size_t)row * 1024 + h * 256 + 4 * lane); gr[h] = ldbf4(F.G16 + (size_t)row * GLAW + 2048 + h * 256 + 4 * lane); }
	s_add_i32 s6, s16, s17
	s_cmp_lt_i32 s6, 0x10000
	s_cbranch_scc0 .Lgf_B_nopf
	s_ashr_i32 s0, s6, 2
	s_ashr_i32 s1, s0, 31
	s_mul_i32 s5, s0, 0x1800
	s_lshl_b64 s[2:3], s[0:1], 12
	s_mul_hi_i32 s4, s0, 0x1800
	v_lshl_add_u64 v[84:85], v[24:25], 0, s[2:3]
	s_add_u32 s0, s20, s5
	global_load_dwordx4 v[96:99], v[84:85], off
	global_load_dwordx4 v[92:95], v[84:85], off offset:1024
	global_load_dwordx4 v[88:91], v[84:85], off offset:2048
	s_waitcnt lgkmcnt(0)
	global_load_dwordx4 v[84:87], v[84:85], off offset:3072
	s_addc_u32 s1, s21, s4
	v_lshl_add_u64 v[100:101], v[22:23], 1, s[0:1]
	v_lshl_add_u64 v[102:103], v[100:101], 0, s[14:15]
	v_add_co_u32_e32 v100, vcc, s18, v100
	global_load_dwordx2 v[104:105], v[102:103], off offset:512
	global_load_dwordx2 v[106:107], v[102:103], off offset:1024
	v_addc_co_u32_e32 v101, vcc, 0, v101, vcc
	global_load_dwordx2 v[100:101], v[100:101], off
	s_nop 0
	global_load_dwordx2 v[102:103], v[102:103], off offset:1536
	s_branch .Lgf_A
.Lgf_B_nopf:
	s_waitcnt vmcnt(4)
	s_branch .Lgf_A
